# v28: v22 + one s_nop at kernel entry (all code shifted 4 bytes: K-loop and attention-loop heads back to the original byte phase mod 8)
# speedup vs baseline: 1.0031x; 1.0031x over previous
; #define LAS __attribute__((address_space(3)))
; DI unsigned xb_add(unsigned* p, unsigned v) { return __hip_atomic_fetch_add(p, v, __ATOMIC_RELAXED, __HIP_MEMORY_SCOPE_AGENT); }
; DI unsigned xb_xcc_id() { return (unsigned)__builtin_amdgcn_s_getreg((3 << 11) | 20) & 0xFu; }
; __global__ void __launch_bounds__(512, 1) mega_kernel(Params p) {
;   __shared__ __attribute__((aligned(16))) char smem[SMEM_BYTES + 16];
;   int* s_item_p = (int*)(smem + SMEM_BYTES);
;   volatile LAS unsigned* xb_st = (volatile LAS unsigned*)(smem + SMEM_BYTES + 8);
;   cg::grid_group grid = cg::this_grid();
;   const int wv = __builtin_amdgcn_readfirstlane(threadIdx.x >> 6);
;   if (xb_leader_lane(wv)) { xb_st[0] = 0u; xb_st[1] = 0u; (void)xb_add(&p.bar[XB_XCNT(xb_xcc_id())], 1u); }
;   __syncthreads();
_Z11mega_kernel6Params:
	s_nop 0
	v_and_b32_e32 v1, 0x3ff, v0
	v_writelane_b32 v253, s2, 0
	s_add_u32 s2, s0, 0x120
	s_addc_u32 s3, s1, 0
	s_load_dwordx4 s[24:27], s[0:1], 0x110
	s_load_dword s80, s[0:1], 0x120
	v_readfirstlane_b32 s6, v1
	v_writelane_b32 v253, s2, 1
	s_cmp_lt_u32 s6, 64
	v_mbcnt_lo_u32_b32 v2, -1, 0
	v_mbcnt_hi_u32_b32 v2, -1, v2
	s_nop 0
	v_writelane_b32 v253, s3, 2
	s_cselect_b64 s[2:3], -1, 0
	v_cmp_eq_u32_e32 vcc, 0, v2
	v_writelane_b32 v253, s2, 3
	s_and_b64 s[4:5], s[2:3], vcc
	s_nop 0
	v_writelane_b32 v253, s3, 4
	s_and_saveexec_b64 s[2:3], s[4:5]
	s_cbranch_execz .LBB0_3
	v_mov_b32_e32 v2, 0
	v_mov_b32_e32 v3, 0x24008
	s_mov_b64 s[4:5], exec
	ds_write_b32 v3, v2
	v_mov_b32_e32 v3, 0x2400c
	ds_write_b32 v3, v2
	v_mbcnt_lo_u32_b32 v2, s4, 0
	v_mbcnt_hi_u32_b32 v2, s5, v2
	v_cmp_eq_u32_e32 vcc, 0, v2
	s_getreg_b32 s7, hwreg(HW_REG_XCC_ID, 0, 4)
	s_and_b64 s[8:9], exec, vcc
	s_mov_b64 exec, s[8:9]
	s_cbranch_execz .LBB0_3
	s_lshl_b32 s7, s7, 8
	s_and_b32 s7, s7, 0xf00
	s_bcnt1_i32_b64 s4, s[4:5]
	v_mov_b32_e32 v2, s7
	v_mov_b32_e32 v3, s4
	s_waitcnt lgkmcnt(0)
	global_atomic_add v2, v3, s[24:25] offset:1024
